# final RMSNorm hand-scheduled: all 16 rows per wave loaded up front (one round trip), same arithmetic
# baseline (speedup 1.0000x reference)
.LBB0_566:
	v_readlane_b32 s0, v252, 34
	s_nop 0
	s_cmp_lg_u32 s0, 0x100
	s_cbranch_scc1 .Lfin_orig
	v_readlane_b32 s1, v252, 48
	v_readfirstlane_b32 s0, v241
	v_readlane_b32 s2, v252, 41
	v_readlane_b32 s3, v252, 42
	v_readlane_b32 s4, v252, 43
	v_readlane_b32 s5, v252, 44
	v_readlane_b32 s6, v252, 45
	v_readlane_b32 s7, v252, 46
	v_and_b32_e32 v59, 63, v241
	v_lshlrev_b32_e32 v56, 5, v59
	v_lshlrev_b32_e32 v57, 4, v59
	v_mov_b32_e32 v58, 0
	v_mov_b32_e32 v35, 0x358637bd
	s_ashr_i32 s0, s0, 6
	s_add_i32 s0, s0, s1
	global_load_dwordx4 v[0:3], v56, s[2:3] offset:2064
	global_load_dwordx4 v[4:7], v56, s[2:3] offset:2048
	global_load_dwordx4 v[8:11], v56, s[2:3] offset:16
	global_load_dwordx4 v[12:15], v56, s[2:3]
	s_lshl_b32 s8, s0, 11
	s_add_u32 s20, s6, 0x5800000
	s_addc_u32 s21, s7, 0
	s_add_u32 s20, s20, s8
	s_addc_u32 s21, s21, 0
	s_lshl_b32 s8, s0, 2
	s_add_u32 s22, s6, 0xc0000
	s_addc_u32 s23, s7, 0
	s_add_u32 s22, s22, s8
	s_addc_u32 s23, s23, 0
	s_lshl_b32 s8, s0, 12
	s_add_u32 s24, s4, s8
	s_addc_u32 s25, s5, 0
	global_load_dwordx4 v[64:67], v57, s[20:21]
	global_load_dwordx4 v[68:71], v57, s[20:21] offset:1024
	global_load_dword v192, v58, s[22:23]
	s_add_u32 s20, s20, 0x400000
	s_addc_u32 s21, s21, 0
	s_add_u32 s22, s22, 0x2000
	s_addc_u32 s23, s23, 0
	global_load_dwordx4 v[72:75], v57, s[20:21]
	global_load_dwordx4 v[76:79], v57, s[20:21] offset:1024
	global_load_dword v193, v58, s[22:23]
	s_add_u32 s20, s20, 0x400000
	s_addc_u32 s21, s21, 0
	s_add_u32 s22, s22, 0x2000
	s_addc_u32 s23, s23, 0
	global_load_dwordx4 v[80:83], v57, s[20:21]
	global_load_dwordx4 v[84:87], v57, s[20:21] offset:1024
	global_load_dword v194, v58, s[22:23]
	s_add_u32 s20, s20, 0x400000
	s_addc_u32 s21, s21, 0
	s_add_u32 s22, s22, 0x2000
	s_addc_u32 s23, s23, 0
	global_load_dwordx4 v[88:91], v57, s[20:21]
	global_load_dwordx4 v[92:95], v57, s[20:21] offset:1024
	global_load_dword v195, v58, s[22:23]
	s_add_u32 s20, s20, 0x400000
	s_addc_u32 s21, s21, 0
	s_add_u32 s22, s22, 0x2000
	s_addc_u32 s23, s23, 0
	global_load_dwordx4 v[96:99], v57, s[20:21]
	global_load_dwordx4 v[100:103], v57, s[20:21] offset:1024
	global_load_dword v196, v58, s[22:23]
	s_add_u32 s20, s20, 0x400000
	s_addc_u32 s21, s21, 0
	s_add_u32 s22, s22, 0x2000
	s_addc_u32 s23, s23, 0
	global_load_dwordx4 v[104:107], v57, s[20:21]
	global_load_dwordx4 v[108:111], v57, s[20:21] offset:1024
	global_load_dword v197, v58, s[22:23]
	s_add_u32 s20, s20, 0x400000
	s_addc_u32 s21, s21, 0
	s_add_u32 s22, s22, 0x2000
	s_addc_u32 s23, s23, 0
	global_load_dwordx4 v[112:115], v57, s[20:21]
	global_load_dwordx4 v[116:119], v57, s[20:21] offset:1024
	global_load_dword v198, v58, s[22:23]
	s_add_u32 s20, s20, 0x400000
	s_addc_u32 s21, s21, 0
	s_add_u32 s22, s22, 0x2000
	s_addc_u32 s23, s23, 0
	global_load_dwordx4 v[120:123], v57, s[20:21]
	global_load_dwordx4 v[124:127], v57, s[20:21] offset:1024
	global_load_dword v199, v58, s[22:23]
	s_add_u32 s20, s20, 0x400000
	s_addc_u32 s21, s21, 0
	s_add_u32 s22, s22, 0x2000
	s_addc_u32 s23, s23, 0
	global_load_dwordx4 v[128:131], v57, s[20:21]
	global_load_dwordx4 v[132:135], v57, s[20:21] offset:1024
	global_load_dword v200, v58, s[22:23]
	s_add_u32 s20, s20, 0x400000
	s_addc_u32 s21, s21, 0
	s_add_u32 s22, s22, 0x2000
	s_addc_u32 s23, s23, 0
	global_load_dwordx4 v[136:139], v57, s[20:21]
	global_load_dwordx4 v[140:143], v57, s[20:21] offset:1024
	global_load_dword v201, v58, s[22:23]
	s_add_u32 s20, s20, 0x400000
	s_addc_u32 s21, s21, 0
	s_add_u32 s22, s22, 0x2000
	s_addc_u32 s23, s23, 0
	global_load_dwordx4 v[144:147], v57, s[20:21]
	global_load_dwordx4 v[148:151], v57, s[20:21] offset:1024
	global_load_dword v202, v58, s[22:23]
	s_add_u32 s20, s20, 0x400000
	s_addc_u32 s21, s21, 0
	s_add_u32 s22, s22, 0x2000
	s_addc_u32 s23, s23, 0
	global_load_dwordx4 v[152:155], v57, s[20:21]
	global_load_dwordx4 v[156:159], v57, s[20:21] offset:1024
	global_load_dword v203, v58, s[22:23]
	s_add_u32 s20, s20, 0x400000
	s_addc_u32 s21, s21, 0
	s_add_u32 s22, s22, 0x2000
	s_addc_u32 s23, s23, 0
	global_load_dwordx4 v[160:163], v57, s[20:21]
	global_load_dwordx4 v[164:167], v57, s[20:21] offset:1024
	global_load_dword v204, v58, s[22:23]
	s_add_u32 s20, s20, 0x400000
	s_addc_u32 s21, s21, 0
	s_add_u32 s22, s22, 0x2000
	s_addc_u32 s23, s23, 0
	global_load_dwordx4 v[168:171], v57, s[20:21]
	global_load_dwordx4 v[172:175], v57, s[20:21] offset:1024
	global_load_dword v205, v58, s[22:23]
	s_add_u32 s20, s20, 0x400000
	s_addc_u32 s21, s21, 0
	s_add_u32 s22, s22, 0x2000
	s_addc_u32 s23, s23, 0
	global_load_dwordx4 v[176:179], v57, s[20:21]
	global_load_dwordx4 v[180:183], v57, s[20:21] offset:1024
	global_load_dword v206, v58, s[22:23]
	s_add_u32 s20, s20, 0x400000
	s_addc_u32 s21, s21, 0
	s_add_u32 s22, s22, 0x2000
	s_addc_u32 s23, s23, 0
	global_load_dwordx4 v[184:187], v57, s[20:21]
	global_load_dwordx4 v[188:191], v57, s[20:21] offset:1024
	global_load_dword v207, v58, s[22:23]
	s_waitcnt vmcnt(45)
	v_cvt_f32_u32_e32 v34, v192
	v_fmamk_f32 v34, v34, 0x35800000, v35
	v_rsq_f32_e32 v32, v34
	v_lshlrev_b32_e32 v16, 16, v64
	v_and_b32_e32 v17, 0xffff0000, v64
	v_lshlrev_b32_e32 v18, 16, v65
	v_and_b32_e32 v19, 0xffff0000, v65
	v_lshlrev_b32_e32 v20, 16, v66
	v_and_b32_e32 v21, 0xffff0000, v66
	v_lshlrev_b32_e32 v22, 16, v67
	v_and_b32_e32 v23, 0xffff0000, v67
	v_lshlrev_b32_e32 v24, 16, v68
	v_and_b32_e32 v25, 0xffff0000, v68
	v_lshlrev_b32_e32 v26, 16, v69
	v_and_b32_e32 v27, 0xffff0000, v69
	v_lshlrev_b32_e32 v28, 16, v70
	v_and_b32_e32 v29, 0xffff0000, v70
	v_lshlrev_b32_e32 v30, 16, v71
	v_and_b32_e32 v31, 0xffff0000, v71
	v_pk_mul_f32 v[16:17], v[32:33], v[16:17] op_sel_hi:[0,1]
	v_pk_mul_f32 v[18:19], v[32:33], v[18:19] op_sel_hi:[0,1]
	v_pk_mul_f32 v[20:21], v[32:33], v[20:21] op_sel_hi:[0,1]
	v_pk_mul_f32 v[22:23], v[32:33], v[22:23] op_sel_hi:[0,1]
	v_pk_mul_f32 v[24:25], v[32:33], v[24:25] op_sel_hi:[0,1]
	v_pk_mul_f32 v[26:27], v[32:33], v[26:27] op_sel_hi:[0,1]
	v_pk_mul_f32 v[28:29], v[32:33], v[28:29] op_sel_hi:[0,1]
	v_pk_mul_f32 v[30:31], v[32:33], v[30:31] op_sel_hi:[0,1]
	v_pk_mul_f32 v[40:41], v[12:13], v[16:17]
	v_pk_mul_f32 v[42:43], v[14:15], v[18:19]
	v_pk_mul_f32 v[44:45], v[8:9], v[20:21]
	v_pk_mul_f32 v[46:47], v[10:11], v[22:23]
	v_pk_mul_f32 v[48:49], v[4:5], v[24:25]
	v_pk_mul_f32 v[50:51], v[6:7], v[26:27]
	v_pk_mul_f32 v[52:53], v[0:1], v[28:29]
	v_pk_mul_f32 v[54:55], v[2:3], v[30:31]
	global_store_dwordx4 v56, v[40:43], s[24:25]
	global_store_dwordx4 v56, v[44:47], s[24:25] offset:16
	global_store_dwordx4 v56, v[48:51], s[24:25] offset:2048
	global_store_dwordx4 v56, v[52:55], s[24:25] offset:2064
	s_add_u32 s24, s24, 0x800000
	s_addc_u32 s25, s25, 0
	s_waitcnt vmcnt(46)
	v_cvt_f32_u32_e32 v34, v193
	v_fmamk_f32 v34, v34, 0x35800000, v35
	v_rsq_f32_e32 v32, v34
	v_lshlrev_b32_e32 v16, 16, v72
	v_and_b32_e32 v17, 0xffff0000, v72
	v_lshlrev_b32_e32 v18, 16, v73
	v_and_b32_e32 v19, 0xffff0000, v73
	v_lshlrev_b32_e32 v20, 16, v74
	v_and_b32_e32 v21, 0xffff0000, v74
	v_lshlrev_b32_e32 v22, 16, v75
	v_and_b32_e32 v23, 0xffff0000, v75
	v_lshlrev_b32_e32 v24, 16, v76
	v_and_b32_e32 v25, 0xffff0000, v76
	v_lshlrev_b32_e32 v26, 16, v77
	v_and_b32_e32 v27, 0xffff0000, v77
	v_lshlrev_b32_e32 v28, 16, v78
	v_and_b32_e32 v29, 0xffff0000, v78
	v_lshlrev_b32_e32 v30, 16, v79
	v_and_b32_e32 v31, 0xffff0000, v79
	v_pk_mul_f32 v[16:17], v[32:33], v[16:17] op_sel_hi:[0,1]
	v_pk_mul_f32 v[18:19], v[32:33], v[18:19] op_sel_hi:[0,1]
	v_pk_mul_f32 v[20:21], v[32:33], v[20:21] op_sel_hi:[0,1]
	v_pk_mul_f32 v[22:23], v[32:33], v[22:23] op_sel_hi:[0,1]
	v_pk_mul_f32 v[24:25], v[32:33], v[24:25] op_sel_hi:[0,1]
	v_pk_mul_f32 v[26:27], v[32:33], v[26:27] op_sel_hi:[0,1]
	v_pk_mul_f32 v[28:29], v[32:33], v[28:29] op_sel_hi:[0,1]
	v_pk_mul_f32 v[30:31], v[32:33], v[30:31] op_sel_hi:[0,1]
	v_pk_mul_f32 v[40:41], v[12:13], v[16:17]
	v_pk_mul_f32 v[42:43], v[14:15], v[18:19]
	v_pk_mul_f32 v[44:45], v[8:9], v[20:21]
	v_pk_mul_f32 v[46:47], v[10:11], v[22:23]
	v_pk_mul_f32 v[48:49], v[4:5], v[24:25]
	v_pk_mul_f32 v[50:51], v[6:7], v[26:27]
	v_pk_mul_f32 v[52:53], v[0:1], v[28:29]
	v_pk_mul_f32 v[54:55], v[2:3], v[30:31]
	global_store_dwordx4 v56, v[40:43], s[24:25]
	global_store_dwordx4 v56, v[44:47], s[24:25] offset:16
	global_store_dwordx4 v56, v[48:51], s[24:25] offset:2048
	global_store_dwordx4 v56, v[52:55], s[24:25] offset:2064
	s_add_u32 s24, s24, 0x800000
	s_addc_u32 s25, s25, 0
	s_waitcnt vmcnt(47)
	v_cvt_f32_u32_e32 v34, v194
	v_fmamk_f32 v34, v34, 0x35800000, v35
	v_rsq_f32_e32 v32, v34
	v_lshlrev_b32_e32 v16, 16, v80
	v_and_b32_e32 v17, 0xffff0000, v80
	v_lshlrev_b32_e32 v18, 16, v81
	v_and_b32_e32 v19, 0xffff0000, v81
	v_lshlrev_b32_e32 v20, 16, v82
	v_and_b32_e32 v21, 0xffff0000, v82
	v_lshlrev_b32_e32 v22, 16, v83
	v_and_b32_e32 v23, 0xffff0000, v83
	v_lshlrev_b32_e32 v24, 16, v84
	v_and_b32_e32 v25, 0xffff0000, v84
	v_lshlrev_b32_e32 v26, 16, v85
	v_and_b32_e32 v27, 0xffff0000, v85
	v_lshlrev_b32_e32 v28, 16, v86
	v_and_b32_e32 v29, 0xffff0000, v86
	v_lshlrev_b32_e32 v30, 16, v87
	v_and_b32_e32 v31, 0xffff0000, v87
	v_pk_mul_f32 v[16:17], v[32:33], v[16:17] op_sel_hi:[0,1]
	v_pk_mul_f32 v[18:19], v[32:33], v[18:19] op_sel_hi:[0,1]
	v_pk_mul_f32 v[20:21], v[32:33], v[20:21] op_sel_hi:[0,1]
	v_pk_mul_f32 v[22:23], v[32:33], v[22:23] op_sel_hi:[0,1]
	v_pk_mul_f32 v[24:25], v[32:33], v[24:25] op_sel_hi:[0,1]
	v_pk_mul_f32 v[26:27], v[32:33], v[26:27] op_sel_hi:[0,1]
	v_pk_mul_f32 v[28:29], v[32:33], v[28:29] op_sel_hi:[0,1]
	v_pk_mul_f32 v[30:31], v[32:33], v[30:31] op_sel_hi:[0,1]
	v_pk_mul_f32 v[40:41], v[12:13], v[16:17]
	v_pk_mul_f32 v[42:43], v[14:15], v[18:19]
	v_pk_mul_f32 v[44:45], v[8:9], v[20:21]
	v_pk_mul_f32 v[46:47], v[10:11], v[22:23]
	v_pk_mul_f32 v[48:49], v[4:5], v[24:25]
	v_pk_mul_f32 v[50:51], v[6:7], v[26:27]
	v_pk_mul_f32 v[52:53], v[0:1], v[28:29]
	v_pk_mul_f32 v[54:55], v[2:3], v[30:31]
	global_store_dwordx4 v56, v[40:43], s[24:25]
	global_store_dwordx4 v56, v[44:47], s[24:25] offset:16
	global_store_dwordx4 v56, v[48:51], s[24:25] offset:2048
	global_store_dwordx4 v56, v[52:55], s[24:25] offset:2064
	s_add_u32 s24, s24, 0x800000
	s_addc_u32 s25, s25, 0
	s_waitcnt vmcnt(48)
	v_cvt_f32_u32_e32 v34, v195
	v_fmamk_f32 v34, v34, 0x35800000, v35
	v_rsq_f32_e32 v32, v34
	v_lshlrev_b32_e32 v16, 16, v88
	v_and_b32_e32 v17, 0xffff0000, v88
	v_lshlrev_b32_e32 v18, 16, v89
	v_and_b32_e32 v19, 0xffff0000, v89
	v_lshlrev_b32_e32 v20, 16, v90
	v_and_b32_e32 v21, 0xffff0000, v90
	v_lshlrev_b32_e32 v22, 16, v91
	v_and_b32_e32 v23, 0xffff0000, v91
	v_lshlrev_b32_e32 v24, 16, v92
	v_and_b32_e32 v25, 0xffff0000, v92
	v_lshlrev_b32_e32 v26, 16, v93
	v_and_b32_e32 v27, 0xffff0000, v93
	v_lshlrev_b32_e32 v28, 16, v94
	v_and_b32_e32 v29, 0xffff0000, v94
	v_lshlrev_b32_e32 v30, 16, v95
	v_and_b32_e32 v31, 0xffff0000, v95
	v_pk_mul_f32 v[16:17], v[32:33], v[16:17] op_sel_hi:[0,1]
	v_pk_mul_f32 v[18:19], v[32:33], v[18:19] op_sel_hi:[0,1]
	v_pk_mul_f32 v[20:21], v[32:33], v[20:21] op_sel_hi:[0,1]
	v_pk_mul_f32 v[22:23], v[32:33], v[22:23] op_sel_hi:[0,1]
	v_pk_mul_f32 v[24:25], v[32:33], v[24:25] op_sel_hi:[0,1]
	v_pk_mul_f32 v[26:27], v[32:33], v[26:27] op_sel_hi:[0,1]
	v_pk_mul_f32 v[28:29], v[32:33], v[28:29] op_sel_hi:[0,1]
	v_pk_mul_f32 v[30:31], v[32:33], v[30:31] op_sel_hi:[0,1]
	v_pk_mul_f32 v[40:41], v[12:13], v[16:17]
	v_pk_mul_f32 v[42:43], v[14:15], v[18:19]
	v_pk_mul_f32 v[44:45], v[8:9], v[20:21]
	v_pk_mul_f32 v[46:47], v[10:11], v[22:23]
	v_pk_mul_f32 v[48:49], v[4:5], v[24:25]
	v_pk_mul_f32 v[50:51], v[6:7], v[26:27]
	v_pk_mul_f32 v[52:53], v[0:1], v[28:29]
	v_pk_mul_f32 v[54:55], v[2:3], v[30:31]
	global_store_dwordx4 v56, v[40:43], s[24:25]
	global_store_dwordx4 v56, v[44:47], s[24:25] offset:16
	global_store_dwordx4 v56, v[48:51], s[24:25] offset:2048
	global_store_dwordx4 v56, v[52:55], s[24:25] offset:2064
	s_add_u32 s24, s24, 0x800000
	s_addc_u32 s25, s25, 0
	s_waitcnt vmcnt(49)
	v_cvt_f32_u32_e32 v34, v196
	v_fmamk_f32 v34, v34, 0x35800000, v35
	v_rsq_f32_e32 v32, v34
	v_lshlrev_b32_e32 v16, 16, v96
	v_and_b32_e32 v17, 0xffff0000, v96
	v_lshlrev_b32_e32 v18, 16, v97
	v_and_b32_e32 v19, 0xffff0000, v97
	v_lshlrev_b32_e32 v20, 16, v98
	v_and_b32_e32 v21, 0xffff0000, v98
	v_lshlrev_b32_e32 v22, 16, v99
	v_and_b32_e32 v23, 0xffff0000, v99
	v_lshlrev_b32_e32 v24, 16, v100
	v_and_b32_e32 v25, 0xffff0000, v100
	v_lshlrev_b32_e32 v26, 16, v101
	v_and_b32_e32 v27, 0xffff0000, v101
	v_lshlrev_b32_e32 v28, 16, v102
	v_and_b32_e32 v29, 0xffff0000, v102
	v_lshlrev_b32_e32 v30, 16, v103
	v_and_b32_e32 v31, 0xffff0000, v103
	v_pk_mul_f32 v[16:17], v[32:33], v[16:17] op_sel_hi:[0,1]
	v_pk_mul_f32 v[18:19], v[32:33], v[18:19] op_sel_hi:[0,1]
	v_pk_mul_f32 v[20:21], v[32:33], v[20:21] op_sel_hi:[0,1]
	v_pk_mul_f32 v[22:23], v[32:33], v[22:23] op_sel_hi:[0,1]
	v_pk_mul_f32 v[24:25], v[32:33], v[24:25] op_sel_hi:[0,1]
	v_pk_mul_f32 v[26:27], v[32:33], v[26:27] op_sel_hi:[0,1]
	v_pk_mul_f32 v[28:29], v[32:33], v[28:29] op_sel_hi:[0,1]
	v_pk_mul_f32 v[30:31], v[32:33], v[30:31] op_sel_hi:[0,1]
	v_pk_mul_f32 v[40:41], v[12:13], v[16:17]
	v_pk_mul_f32 v[42:43], v[14:15], v[18:19]
	v_pk_mul_f32 v[44:45], v[8:9], v[20:21]
	v_pk_mul_f32 v[46:47], v[10:11], v[22:23]
	v_pk_mul_f32 v[48:49], v[4:5], v[24:25]
	v_pk_mul_f32 v[50:51], v[6:7], v[26:27]
	v_pk_mul_f32 v[52:53], v[0:1], v[28:29]
	v_pk_mul_f32 v[54:55], v[2:3], v[30:31]
	global_store_dwordx4 v56, v[40:43], s[24:25]
	global_store_dwordx4 v56, v[44:47], s[24:25] offset:16
	global_store_dwordx4 v56, v[48:51], s[24:25] offset:2048
	global_store_dwordx4 v56, v[52:55], s[24:25] offset:2064
	s_add_u32 s24, s24, 0x800000
	s_addc_u32 s25, s25, 0
	s_waitcnt vmcnt(50)
	v_cvt_f32_u32_e32 v34, v197
	v_fmamk_f32 v34, v34, 0x35800000, v35
	v_rsq_f32_e32 v32, v34
	v_lshlrev_b32_e32 v16, 16, v104
	v_and_b32_e32 v17, 0xffff0000, v104
	v_lshlrev_b32_e32 v18, 16, v105
	v_and_b32_e32 v19, 0xffff0000, v105
	v_lshlrev_b32_e32 v20, 16, v106
	v_and_b32_e32 v21, 0xffff0000, v106
	v_lshlrev_b32_e32 v22, 16, v107
	v_and_b32_e32 v23, 0xffff0000, v107
	v_lshlrev_b32_e32 v24, 16, v108
	v_and_b32_e32 v25, 0xffff0000, v108
	v_lshlrev_b32_e32 v26, 16, v109
	v_and_b32_e32 v27, 0xffff0000, v109
	v_lshlrev_b32_e32 v28, 16, v110
	v_and_b32_e32 v29, 0xffff0000, v110
	v_lshlrev_b32_e32 v30, 16, v111
	v_and_b32_e32 v31, 0xffff0000, v111
	v_pk_mul_f32 v[16:17], v[32:33], v[16:17] op_sel_hi:[0,1]
	v_pk_mul_f32 v[18:19], v[32:33], v[18:19] op_sel_hi:[0,1]
	v_pk_mul_f32 v[20:21], v[32:33], v[20:21] op_sel_hi:[0,1]
	v_pk_mul_f32 v[22:23], v[32:33], v[22:23] op_sel_hi:[0,1]
	v_pk_mul_f32 v[24:25], v[32:33], v[24:25] op_sel_hi:[0,1]
	v_pk_mul_f32 v[26:27], v[32:33], v[26:27] op_sel_hi:[0,1]
	v_pk_mul_f32 v[28:29], v[32:33], v[28:29] op_sel_hi:[0,1]
	v_pk_mul_f32 v[30:31], v[32:33], v[30:31] op_sel_hi:[0,1]
	v_pk_mul_f32 v[40:41], v[12:13], v[16:17]
	v_pk_mul_f32 v[42:43], v[14:15], v[18:19]
	v_pk_mul_f32 v[44:45], v[8:9], v[20:21]
	v_pk_mul_f32 v[46:47], v[10:11], v[22:23]
	v_pk_mul_f32 v[48:49], v[4:5], v[24:25]
	v_pk_mul_f32 v[50:51], v[6:7], v[26:27]
	v_pk_mul_f32 v[52:53], v[0:1], v[28:29]
	v_pk_mul_f32 v[54:55], v[2:3], v[30:31]
	global_store_dwordx4 v56, v[40:43], s[24:25]
	global_store_dwordx4 v56, v[44:47], s[24:25] offset:16
	global_store_dwordx4 v56, v[48:51], s[24:25] offset:2048
	global_store_dwordx4 v56, v[52:55], s[24:25] offset:2064
	s_add_u32 s24, s24, 0x800000
	s_addc_u32 s25, s25, 0
	s_waitcnt vmcnt(51)
	v_cvt_f32_u32_e32 v34, v198
	v_fmamk_f32 v34, v34, 0x35800000, v35
	v_rsq_f32_e32 v32, v34
	v_lshlrev_b32_e32 v16, 16, v112
	v_and_b32_e32 v17, 0xffff0000, v112
	v_lshlrev_b32_e32 v18, 16, v113
	v_and_b32_e32 v19, 0xffff0000, v113
	v_lshlrev_b32_e32 v20, 16, v114
	v_and_b32_e32 v21, 0xffff0000, v114
	v_lshlrev_b32_e32 v22, 16, v115
	v_and_b32_e32 v23, 0xffff0000, v115
	v_lshlrev_b32_e32 v24, 16, v116
	v_and_b32_e32 v25, 0xffff0000, v116
	v_lshlrev_b32_e32 v26, 16, v117
	v_and_b32_e32 v27, 0xffff0000, v117
	v_lshlrev_b32_e32 v28, 16, v118
	v_and_b32_e32 v29, 0xffff0000, v118
	v_lshlrev_b32_e32 v30, 16, v119
	v_and_b32_e32 v31, 0xffff0000, v119
	v_pk_mul_f32 v[16:17], v[32:33], v[16:17] op_sel_hi:[0,1]
	v_pk_mul_f32 v[18:19], v[32:33], v[18:19] op_sel_hi:[0,1]
	v_pk_mul_f32 v[20:21], v[32:33], v[20:21] op_sel_hi:[0,1]
	v_pk_mul_f32 v[22:23], v[32:33], v[22:23] op_sel_hi:[0,1]
	v_pk_mul_f32 v[24:25], v[32:33], v[24:25] op_sel_hi:[0,1]
	v_pk_mul_f32 v[26:27], v[32:33], v[26:27] op_sel_hi:[0,1]
	v_pk_mul_f32 v[28:29], v[32:33], v[28:29] op_sel_hi:[0,1]
	v_pk_mul_f32 v[30:31], v[32:33], v[30:31] op_sel_hi:[0,1]
	v_pk_mul_f32 v[40:41], v[12:13], v[16:17]
	v_pk_mul_f32 v[42:43], v[14:15], v[18:19]
	v_pk_mul_f32 v[44:45], v[8:9], v[20:21]
	v_pk_mul_f32 v[46:47], v[10:11], v[22:23]
	v_pk_mul_f32 v[48:49], v[4:5], v[24:25]
	v_pk_mul_f32 v[50:51], v[6:7], v[26:27]
	v_pk_mul_f32 v[52:53], v[0:1], v[28:29]
	v_pk_mul_f32 v[54:55], v[2:3], v[30:31]
	global_store_dwordx4 v56, v[40:43], s[24:25]
	global_store_dwordx4 v56, v[44:47], s[24:25] offset:16
	global_store_dwordx4 v56, v[48:51], s[24:25] offset:2048
	global_store_dwordx4 v56, v[52:55], s[24:25] offset:2064
	s_add_u32 s24, s24, 0x800000
	s_addc_u32 s25, s25, 0
	s_waitcnt vmcnt(52)
	v_cvt_f32_u32_e32 v34, v199
	v_fmamk_f32 v34, v34, 0x35800000, v35
	v_rsq_f32_e32 v32, v34
	v_lshlrev_b32_e32 v16, 16, v120
	v_and_b32_e32 v17, 0xffff0000, v120
	v_lshlrev_b32_e32 v18, 16, v121
	v_and_b32_e32 v19, 0xffff0000, v121
	v_lshlrev_b32_e32 v20, 16, v122
	v_and_b32_e32 v21, 0xffff0000, v122
	v_lshlrev_b32_e32 v22, 16, v123
	v_and_b32_e32 v23, 0xffff0000, v123
	v_lshlrev_b32_e32 v24, 16, v124
	v_and_b32_e32 v25, 0xffff0000, v124
	v_lshlrev_b32_e32 v26, 16, v125
	v_and_b32_e32 v27, 0xffff0000, v125
	v_lshlrev_b32_e32 v28, 16, v126
	v_and_b32_e32 v29, 0xffff0000, v126
	v_lshlrev_b32_e32 v30, 16, v127
	v_and_b32_e32 v31, 0xffff0000, v127
	v_pk_mul_f32 v[16:17], v[32:33], v[16:17] op_sel_hi:[0,1]
	v_pk_mul_f32 v[18:19], v[32:33], v[18:19] op_sel_hi:[0,1]
	v_pk_mul_f32 v[20:21], v[32:33], v[20:21] op_sel_hi:[0,1]
	v_pk_mul_f32 v[22:23], v[32:33], v[22:23] op_sel_hi:[0,1]
	v_pk_mul_f32 v[24:25], v[32:33], v[24:25] op_sel_hi:[0,1]
	v_pk_mul_f32 v[26:27], v[32:33], v[26:27] op_sel_hi:[0,1]
	v_pk_mul_f32 v[28:29], v[32:33], v[28:29] op_sel_hi:[0,1]
	v_pk_mul_f32 v[30:31], v[32:33], v[30:31] op_sel_hi:[0,1]
	v_pk_mul_f32 v[40:41], v[12:13], v[16:17]
	v_pk_mul_f32 v[42:43], v[14:15], v[18:19]
	v_pk_mul_f32 v[44:45], v[8:9], v[20:21]
	v_pk_mul_f32 v[46:47], v[10:11], v[22:23]
	v_pk_mul_f32 v[48:49], v[4:5], v[24:25]
	v_pk_mul_f32 v[50:51], v[6:7], v[26:27]
	v_pk_mul_f32 v[52:53], v[0:1], v[28:29]
	v_pk_mul_f32 v[54:55], v[2:3], v[30:31]
	global_store_dwordx4 v56, v[40:43], s[24:25]
	global_store_dwordx4 v56, v[44:47], s[24:25] offset:16
	global_store_dwordx4 v56, v[48:51], s[24:25] offset:2048
	global_store_dwordx4 v56, v[52:55], s[24:25] offset:2064
	s_add_u32 s24, s24, 0x800000
	s_addc_u32 s25, s25, 0
	s_waitcnt vmcnt(53)
	v_cvt_f32_u32_e32 v34, v200
	v_fmamk_f32 v34, v34, 0x35800000, v35
	v_rsq_f32_e32 v32, v34
	v_lshlrev_b32_e32 v16, 16, v128
	v_and_b32_e32 v17, 0xffff0000, v128
	v_lshlrev_b32_e32 v18, 16, v129
	v_and_b32_e32 v19, 0xffff0000, v129
	v_lshlrev_b32_e32 v20, 16, v130
	v_and_b32_e32 v21, 0xffff0000, v130
	v_lshlrev_b32_e32 v22, 16, v131
	v_and_b32_e32 v23, 0xffff0000, v131
	v_lshlrev_b32_e32 v24, 16, v132
	v_and_b32_e32 v25, 0xffff0000, v132
	v_lshlrev_b32_e32 v26, 16, v133
	v_and_b32_e32 v27, 0xffff0000, v133
	v_lshlrev_b32_e32 v28, 16, v134
	v_and_b32_e32 v29, 0xffff0000, v134
	v_lshlrev_b32_e32 v30, 16, v135
	v_and_b32_e32 v31, 0xffff0000, v135
	v_pk_mul_f32 v[16:17], v[32:33], v[16:17] op_sel_hi:[0,1]
	v_pk_mul_f32 v[18:19], v[32:33], v[18:19] op_sel_hi:[0,1]
	v_pk_mul_f32 v[20:21], v[32:33], v[20:21] op_sel_hi:[0,1]
	v_pk_mul_f32 v[22:23], v[32:33], v[22:23] op_sel_hi:[0,1]
	v_pk_mul_f32 v[24:25], v[32:33], v[24:25] op_sel_hi:[0,1]
	v_pk_mul_f32 v[26:27], v[32:33], v[26:27] op_sel_hi:[0,1]
	v_pk_mul_f32 v[28:29], v[32:33], v[28:29] op_sel_hi:[0,1]
	v_pk_mul_f32 v[30:31], v[32:33], v[30:31] op_sel_hi:[0,1]
	v_pk_mul_f32 v[40:41], v[12:13], v[16:17]
	v_pk_mul_f32 v[42:43], v[14:15], v[18:19]
	v_pk_mul_f32 v[44:45], v[8:9], v[20:21]
	v_pk_mul_f32 v[46:47], v[10:11], v[22:23]
	v_pk_mul_f32 v[48:49], v[4:5], v[24:25]
	v_pk_mul_f32 v[50:51], v[6:7], v[26:27]
	v_pk_mul_f32 v[52:53], v[0:1], v[28:29]
	v_pk_mul_f32 v[54:55], v[2:3], v[30:31]
	global_store_dwordx4 v56, v[40:43], s[24:25]
	global_store_dwordx4 v56, v[44:47], s[24:25] offset:16
	global_store_dwordx4 v56, v[48:51], s[24:25] offset:2048
	global_store_dwordx4 v56, v[52:55], s[24:25] offset:2064
	s_add_u32 s24, s24, 0x800000
	s_addc_u32 s25, s25, 0
	s_waitcnt vmcnt(54)
	v_cvt_f32_u32_e32 v34, v201
	v_fmamk_f32 v34, v34, 0x35800000, v35
	v_rsq_f32_e32 v32, v34
	v_lshlrev_b32_e32 v16, 16, v136
	v_and_b32_e32 v17, 0xffff0000, v136
	v_lshlrev_b32_e32 v18, 16, v137
	v_and_b32_e32 v19, 0xffff0000, v137
	v_lshlrev_b32_e32 v20, 16, v138
	v_and_b32_e32 v21, 0xffff0000, v138
	v_lshlrev_b32_e32 v22, 16, v139
	v_and_b32_e32 v23, 0xffff0000, v139
	v_lshlrev_b32_e32 v24, 16, v140
	v_and_b32_e32 v25, 0xffff0000, v140
	v_lshlrev_b32_e32 v26, 16, v141
	v_and_b32_e32 v27, 0xffff0000, v141
	v_lshlrev_b32_e32 v28, 16, v142
	v_and_b32_e32 v29, 0xffff0000, v142
	v_lshlrev_b32_e32 v30, 16, v143
	v_and_b32_e32 v31, 0xffff0000, v143
	v_pk_mul_f32 v[16:17], v[32:33], v[16:17] op_sel_hi:[0,1]
	v_pk_mul_f32 v[18:19], v[32:33], v[18:19] op_sel_hi:[0,1]
	v_pk_mul_f32 v[20:21], v[32:33], v[20:21] op_sel_hi:[0,1]
	v_pk_mul_f32 v[22:23], v[32:33], v[22:23] op_sel_hi:[0,1]
	v_pk_mul_f32 v[24:25], v[32:33], v[24:25] op_sel_hi:[0,1]
	v_pk_mul_f32 v[26:27], v[32:33], v[26:27] op_sel_hi:[0,1]
	v_pk_mul_f32 v[28:29], v[32:33], v[28:29] op_sel_hi:[0,1]
	v_pk_mul_f32 v[30:31], v[32:33], v[30:31] op_sel_hi:[0,1]
	v_pk_mul_f32 v[40:41], v[12:13], v[16:17]
	v_pk_mul_f32 v[42:43], v[14:15], v[18:19]
	v_pk_mul_f32 v[44:45], v[8:9], v[20:21]
	v_pk_mul_f32 v[46:47], v[10:11], v[22:23]
	v_pk_mul_f32 v[48:49], v[4:5], v[24:25]
	v_pk_mul_f32 v[50:51], v[6:7], v[26:27]
	v_pk_mul_f32 v[52:53], v[0:1], v[28:29]
	v_pk_mul_f32 v[54:55], v[2:3], v[30:31]
	global_store_dwordx4 v56, v[40:43], s[24:25]
	global_store_dwordx4 v56, v[44:47], s[24:25] offset:16
	global_store_dwordx4 v56, v[48:51], s[24:25] offset:2048
	global_store_dwordx4 v56, v[52:55], s[24:25] offset:2064
	s_add_u32 s24, s24, 0x800000
	s_addc_u32 s25, s25, 0
	s_waitcnt vmcnt(55)
	v_cvt_f32_u32_e32 v34, v202
	v_fmamk_f32 v34, v34, 0x35800000, v35
	v_rsq_f32_e32 v32, v34
	v_lshlrev_b32_e32 v16, 16, v144
	v_and_b32_e32 v17, 0xffff0000, v144
	v_lshlrev_b32_e32 v18, 16, v145
	v_and_b32_e32 v19, 0xffff0000, v145
	v_lshlrev_b32_e32 v20, 16, v146
	v_and_b32_e32 v21, 0xffff0000, v146
	v_lshlrev_b32_e32 v22, 16, v147
	v_and_b32_e32 v23, 0xffff0000, v147
	v_lshlrev_b32_e32 v24, 16, v148
	v_and_b32_e32 v25, 0xffff0000, v148
	v_lshlrev_b32_e32 v26, 16, v149
	v_and_b32_e32 v27, 0xffff0000, v149
	v_lshlrev_b32_e32 v28, 16, v150
	v_and_b32_e32 v29, 0xffff0000, v150
	v_lshlrev_b32_e32 v30, 16, v151
	v_and_b32_e32 v31, 0xffff0000, v151
	v_pk_mul_f32 v[16:17], v[32:33], v[16:17] op_sel_hi:[0,1]
	v_pk_mul_f32 v[18:19], v[32:33], v[18:19] op_sel_hi:[0,1]
	v_pk_mul_f32 v[20:21], v[32:33], v[20:21] op_sel_hi:[0,1]
	v_pk_mul_f32 v[22:23], v[32:33], v[22:23] op_sel_hi:[0,1]
	v_pk_mul_f32 v[24:25], v[32:33], v[24:25] op_sel_hi:[0,1]
	v_pk_mul_f32 v[26:27], v[32:33], v[26:27] op_sel_hi:[0,1]
	v_pk_mul_f32 v[28:29], v[32:33], v[28:29] op_sel_hi:[0,1]
	v_pk_mul_f32 v[30:31], v[32:33], v[30:31] op_sel_hi:[0,1]
	v_pk_mul_f32 v[40:41], v[12:13], v[16:17]
	v_pk_mul_f32 v[42:43], v[14:15], v[18:19]
	v_pk_mul_f32 v[44:45], v[8:9], v[20:21]
	v_pk_mul_f32 v[46:47], v[10:11], v[22:23]
	v_pk_mul_f32 v[48:49], v[4:5], v[24:25]
	v_pk_mul_f32 v[50:51], v[6:7], v[26:27]
	v_pk_mul_f32 v[52:53], v[0:1], v[28:29]
	v_pk_mul_f32 v[54:55], v[2:3], v[30:31]
	global_store_dwordx4 v56, v[40:43], s[24:25]
	global_store_dwordx4 v56, v[44:47], s[24:25] offset:16
	global_store_dwordx4 v56, v[48:51], s[24:25] offset:2048
	global_store_dwordx4 v56, v[52:55], s[24:25] offset:2064
	s_add_u32 s24, s24, 0x800000
	s_addc_u32 s25, s25, 0
	s_waitcnt vmcnt(56)
	v_cvt_f32_u32_e32 v34, v203
	v_fmamk_f32 v34, v34, 0x35800000, v35
	v_rsq_f32_e32 v32, v34
	v_lshlrev_b32_e32 v16, 16, v152
	v_and_b32_e32 v17, 0xffff0000, v152
	v_lshlrev_b32_e32 v18, 16, v153
	v_and_b32_e32 v19, 0xffff0000, v153
	v_lshlrev_b32_e32 v20, 16, v154
	v_and_b32_e32 v21, 0xffff0000, v154
	v_lshlrev_b32_e32 v22, 16, v155
	v_and_b32_e32 v23, 0xffff0000, v155
	v_lshlrev_b32_e32 v24, 16, v156
	v_and_b32_e32 v25, 0xffff0000, v156
	v_lshlrev_b32_e32 v26, 16, v157
	v_and_b32_e32 v27, 0xffff0000, v157
	v_lshlrev_b32_e32 v28, 16, v158
	v_and_b32_e32 v29, 0xffff0000, v158
	v_lshlrev_b32_e32 v30, 16, v159
	v_and_b32_e32 v31, 0xffff0000, v159
	v_pk_mul_f32 v[16:17], v[32:33], v[16:17] op_sel_hi:[0,1]
	v_pk_mul_f32 v[18:19], v[32:33], v[18:19] op_sel_hi:[0,1]
	v_pk_mul_f32 v[20:21], v[32:33], v[20:21] op_sel_hi:[0,1]
	v_pk_mul_f32 v[22:23], v[32:33], v[22:23] op_sel_hi:[0,1]
	v_pk_mul_f32 v[24:25], v[32:33], v[24:25] op_sel_hi:[0,1]
	v_pk_mul_f32 v[26:27], v[32:33], v[26:27] op_sel_hi:[0,1]
	v_pk_mul_f32 v[28:29], v[32:33], v[28:29] op_sel_hi:[0,1]
	v_pk_mul_f32 v[30:31], v[32:33], v[30:31] op_sel_hi:[0,1]
	v_pk_mul_f32 v[40:41], v[12:13], v[16:17]
	v_pk_mul_f32 v[42:43], v[14:15], v[18:19]
	v_pk_mul_f32 v[44:45], v[8:9], v[20:21]
	v_pk_mul_f32 v[46:47], v[10:11], v[22:23]
	v_pk_mul_f32 v[48:49], v[4:5], v[24:25]
	v_pk_mul_f32 v[50:51], v[6:7], v[26:27]
	v_pk_mul_f32 v[52:53], v[0:1], v[28:29]
	v_pk_mul_f32 v[54:55], v[2:3], v[30:31]
	global_store_dwordx4 v56, v[40:43], s[24:25]
	global_store_dwordx4 v56, v[44:47], s[24:25] offset:16
	global_store_dwordx4 v56, v[48:51], s[24:25] offset:2048
	global_store_dwordx4 v56, v[52:55], s[24:25] offset:2064
	s_add_u32 s24, s24, 0x800000
	s_addc_u32 s25, s25, 0
	s_waitcnt vmcnt(57)
	v_cvt_f32_u32_e32 v34, v204
	v_fmamk_f32 v34, v34, 0x35800000, v35
	v_rsq_f32_e32 v32, v34
	v_lshlrev_b32_e32 v16, 16, v160
	v_and_b32_e32 v17, 0xffff0000, v160
	v_lshlrev_b32_e32 v18, 16, v161
	v_and_b32_e32 v19, 0xffff0000, v161
	v_lshlrev_b32_e32 v20, 16, v162
	v_and_b32_e32 v21, 0xffff0000, v162
	v_lshlrev_b32_e32 v22, 16, v163
	v_and_b32_e32 v23, 0xffff0000, v163
	v_lshlrev_b32_e32 v24, 16, v164
	v_and_b32_e32 v25, 0xffff0000, v164
	v_lshlrev_b32_e32 v26, 16, v165
	v_and_b32_e32 v27, 0xffff0000, v165
	v_lshlrev_b32_e32 v28, 16, v166
	v_and_b32_e32 v29, 0xffff0000, v166
	v_lshlrev_b32_e32 v30, 16, v167
	v_and_b32_e32 v31, 0xffff0000, v167
	v_pk_mul_f32 v[16:17], v[32:33], v[16:17] op_sel_hi:[0,1]
	v_pk_mul_f32 v[18:19], v[32:33], v[18:19] op_sel_hi:[0,1]
	v_pk_mul_f32 v[20:21], v[32:33], v[20:21] op_sel_hi:[0,1]
	v_pk_mul_f32 v[22:23], v[32:33], v[22:23] op_sel_hi:[0,1]
	v_pk_mul_f32 v[24:25], v[32:33], v[24:25] op_sel_hi:[0,1]
	v_pk_mul_f32 v[26:27], v[32:33], v[26:27] op_sel_hi:[0,1]
	v_pk_mul_f32 v[28:29], v[32:33], v[28:29] op_sel_hi:[0,1]
	v_pk_mul_f32 v[30:31], v[32:33], v[30:31] op_sel_hi:[0,1]
	v_pk_mul_f32 v[40:41], v[12:13], v[16:17]
	v_pk_mul_f32 v[42:43], v[14:15], v[18:19]
	v_pk_mul_f32 v[44:45], v[8:9], v[20:21]
	v_pk_mul_f32 v[46:47], v[10:11], v[22:23]
	v_pk_mul_f32 v[48:49], v[4:5], v[24:25]
	v_pk_mul_f32 v[50:51], v[6:7], v[26:27]
	v_pk_mul_f32 v[52:53], v[0:1], v[28:29]
	v_pk_mul_f32 v[54:55], v[2:3], v[30:31]
	global_store_dwordx4 v56, v[40:43], s[24:25]
	global_store_dwordx4 v56, v[44:47], s[24:25] offset:16
	global_store_dwordx4 v56, v[48:51], s[24:25] offset:2048
	global_store_dwordx4 v56, v[52:55], s[24:25] offset:2064
	s_add_u32 s24, s24, 0x800000
	s_addc_u32 s25, s25, 0
	s_waitcnt vmcnt(58)
	v_cvt_f32_u32_e32 v34, v205
	v_fmamk_f32 v34, v34, 0x35800000, v35
	v_rsq_f32_e32 v32, v34
	v_lshlrev_b32_e32 v16, 16, v168
	v_and_b32_e32 v17, 0xffff0000, v168
	v_lshlrev_b32_e32 v18, 16, v169
	v_and_b32_e32 v19, 0xffff0000, v169
	v_lshlrev_b32_e32 v20, 16, v170
	v_and_b32_e32 v21, 0xffff0000, v170
	v_lshlrev_b32_e32 v22, 16, v171
	v_and_b32_e32 v23, 0xffff0000, v171
	v_lshlrev_b32_e32 v24, 16, v172
	v_and_b32_e32 v25, 0xffff0000, v172
	v_lshlrev_b32_e32 v26, 16, v173
	v_and_b32_e32 v27, 0xffff0000, v173
	v_lshlrev_b32_e32 v28, 16, v174
	v_and_b32_e32 v29, 0xffff0000, v174
	v_lshlrev_b32_e32 v30, 16, v175
	v_and_b32_e32 v31, 0xffff0000, v175
	v_pk_mul_f32 v[16:17], v[32:33], v[16:17] op_sel_hi:[0,1]
	v_pk_mul_f32 v[18:19], v[32:33], v[18:19] op_sel_hi:[0,1]
	v_pk_mul_f32 v[20:21], v[32:33], v[20:21] op_sel_hi:[0,1]
	v_pk_mul_f32 v[22:23], v[32:33], v[22:23] op_sel_hi:[0,1]
	v_pk_mul_f32 v[24:25], v[32:33], v[24:25] op_sel_hi:[0,1]
	v_pk_mul_f32 v[26:27], v[32:33], v[26:27] op_sel_hi:[0,1]
	v_pk_mul_f32 v[28:29], v[32:33], v[28:29] op_sel_hi:[0,1]
	v_pk_mul_f32 v[30:31], v[32:33], v[30:31] op_sel_hi:[0,1]
	v_pk_mul_f32 v[40:41], v[12:13], v[16:17]
	v_pk_mul_f32 v[42:43], v[14:15], v[18:19]
	v_pk_mul_f32 v[44:45], v[8:9], v[20:21]
	v_pk_mul_f32 v[46:47], v[10:11], v[22:23]
	v_pk_mul_f32 v[48:49], v[4:5], v[24:25]
	v_pk_mul_f32 v[50:51], v[6:7], v[26:27]
	v_pk_mul_f32 v[52:53], v[0:1], v[28:29]
	v_pk_mul_f32 v[54:55], v[2:3], v[30:31]
	global_store_dwordx4 v56, v[40:43], s[24:25]
	global_store_dwordx4 v56, v[44:47], s[24:25] offset:16
	global_store_dwordx4 v56, v[48:51], s[24:25] offset:2048
	global_store_dwordx4 v56, v[52:55], s[24:25] offset:2064
	s_add_u32 s24, s24, 0x800000
	s_addc_u32 s25, s25, 0
	s_waitcnt vmcnt(59)
	v_cvt_f32_u32_e32 v34, v206
	v_fmamk_f32 v34, v34, 0x35800000, v35
	v_rsq_f32_e32 v32, v34
	v_lshlrev_b32_e32 v16, 16, v176
	v_and_b32_e32 v17, 0xffff0000, v176
	v_lshlrev_b32_e32 v18, 16, v177
	v_and_b32_e32 v19, 0xffff0000, v177
	v_lshlrev_b32_e32 v20, 16, v178
	v_and_b32_e32 v21, 0xffff0000, v178
	v_lshlrev_b32_e32 v22, 16, v179
	v_and_b32_e32 v23, 0xffff0000, v179
	v_lshlrev_b32_e32 v24, 16, v180
	v_and_b32_e32 v25, 0xffff0000, v180
	v_lshlrev_b32_e32 v26, 16, v181
	v_and_b32_e32 v27, 0xffff0000, v181
	v_lshlrev_b32_e32 v28, 16, v182
	v_and_b32_e32 v29, 0xffff0000, v182
	v_lshlrev_b32_e32 v30, 16, v183
	v_and_b32_e32 v31, 0xffff0000, v183
	v_pk_mul_f32 v[16:17], v[32:33], v[16:17] op_sel_hi:[0,1]
	v_pk_mul_f32 v[18:19], v[32:33], v[18:19] op_sel_hi:[0,1]
	v_pk_mul_f32 v[20:21], v[32:33], v[20:21] op_sel_hi:[0,1]
	v_pk_mul_f32 v[22:23], v[32:33], v[22:23] op_sel_hi:[0,1]
	v_pk_mul_f32 v[24:25], v[32:33], v[24:25] op_sel_hi:[0,1]
	v_pk_mul_f32 v[26:27], v[32:33], v[26:27] op_sel_hi:[0,1]
	v_pk_mul_f32 v[28:29], v[32:33], v[28:29] op_sel_hi:[0,1]
	v_pk_mul_f32 v[30:31], v[32:33], v[30:31] op_sel_hi:[0,1]
	v_pk_mul_f32 v[40:41], v[12:13], v[16:17]
	v_pk_mul_f32 v[42:43], v[14:15], v[18:19]
	v_pk_mul_f32 v[44:45], v[8:9], v[20:21]
	v_pk_mul_f32 v[46:47], v[10:11], v[22:23]
	v_pk_mul_f32 v[48:49], v[4:5], v[24:25]
	v_pk_mul_f32 v[50:51], v[6:7], v[26:27]
	v_pk_mul_f32 v[52:53], v[0:1], v[28:29]
	v_pk_mul_f32 v[54:55], v[2:3], v[30:31]
	global_store_dwordx4 v56, v[40:43], s[24:25]
	global_store_dwordx4 v56, v[44:47], s[24:25] offset:16
	global_store_dwordx4 v56, v[48:51], s[24:25] offset:2048
	global_store_dwordx4 v56, v[52:55], s[24:25] offset:2064
	s_add_u32 s24, s24, 0x800000
	s_addc_u32 s25, s25, 0
	s_waitcnt vmcnt(60)
	v_cvt_f32_u32_e32 v34, v207
	v_fmamk_f32 v34, v34, 0x35800000, v35
	v_rsq_f32_e32 v32, v34
	v_lshlrev_b32_e32 v16, 16, v184
	v_and_b32_e32 v17, 0xffff0000, v184
	v_lshlrev_b32_e32 v18, 16, v185
	v_and_b32_e32 v19, 0xffff0000, v185
	v_lshlrev_b32_e32 v20, 16, v186
	v_and_b32_e32 v21, 0xffff0000, v186
	v_lshlrev_b32_e32 v22, 16, v187
	v_and_b32_e32 v23, 0xffff0000, v187
	v_lshlrev_b32_e32 v24, 16, v188
	v_and_b32_e32 v25, 0xffff0000, v188
	v_lshlrev_b32_e32 v26, 16, v189
	v_and_b32_e32 v27, 0xffff0000, v189
	v_lshlrev_b32_e32 v28, 16, v190
	v_and_b32_e32 v29, 0xffff0000, v190
	v_lshlrev_b32_e32 v30, 16, v191
	v_and_b32_e32 v31, 0xffff0000, v191
	v_pk_mul_f32 v[16:17], v[32:33], v[16:17] op_sel_hi:[0,1]
	v_pk_mul_f32 v[18:19], v[32:33], v[18:19] op_sel_hi:[0,1]
	v_pk_mul_f32 v[20:21], v[32:33], v[20:21] op_sel_hi:[0,1]
	v_pk_mul_f32 v[22:23], v[32:33], v[22:23] op_sel_hi:[0,1]
	v_pk_mul_f32 v[24:25], v[32:33], v[24:25] op_sel_hi:[0,1]
	v_pk_mul_f32 v[26:27], v[32:33], v[26:27] op_sel_hi:[0,1]
	v_pk_mul_f32 v[28:29], v[32:33], v[28:29] op_sel_hi:[0,1]
	v_pk_mul_f32 v[30:31], v[32:33], v[30:31] op_sel_hi:[0,1]
	v_pk_mul_f32 v[40:41], v[12:13], v[16:17]
	v_pk_mul_f32 v[42:43], v[14:15], v[18:19]
	v_pk_mul_f32 v[44:45], v[8:9], v[20:21]
	v_pk_mul_f32 v[46:47], v[10:11], v[22:23]
	v_pk_mul_f32 v[48:49], v[4:5], v[24:25]
	v_pk_mul_f32 v[50:51], v[6:7], v[26:27]
	v_pk_mul_f32 v[52:53], v[0:1], v[28:29]
	v_pk_mul_f32 v[54:55], v[2:3], v[30:31]
	global_store_dwordx4 v56, v[40:43], s[24:25]
	global_store_dwordx4 v56, v[44:47], s[24:25] offset:16
	global_store_dwordx4 v56, v[48:51], s[24:25] offset:2048
	global_store_dwordx4 v56, v[52:55], s[24:25] offset:2064
	s_branch .LBB0_575
